# ssdc: x^T tile loads issued together with the C/B loads (one memory round trip less per item)
# speedup vs baseline: 1.0168x; 1.0057x over previous
; #define LAS __attribute__((address_space(3)))
; __device__ __forceinline__ int ltid() { int t = threadIdx.x; asm volatile("" : "+v"(t)); return t; }
; __device__ __forceinline__ void ph_ssdc(LAS unsigned char* lds) {
;     ...
;         const int bl = item, g = item & 7, c = (item >> 3) & 31, b = item >> 8;
;         const int trow0 = b * SEQ + c * 128;
;         bf16x8 hpf[2][8];
; #pragma unroll
;         for (int pb = 0; pb < 2; ++pb) { const bf16_t* hp = (const bf16_t*)(ws + WS_HP) + ((size_t)bl * 4 + h) * 8192 + (unsigned)((pb * 32 + r32) * 128 + hf * 8);
; #pragma unroll
;             for (int ks = 0; ks < 8; ++ks) hpf[pb][ks] = *(const bf16x8*)(hp + ks * 16); }
;         {
;             int tid = ltid(); const int lane = tid & 63;
;             const bf16_t* cc = (const bf16_t*)(ws + WS_CC) + (size_t)bl * 16384; const bf16_t* bc = (const bf16_t*)(ws + WS_BC) + (size_t)bl * 16384; const bf16_t* xt = (const bf16_t*)(ws + WS_XT) + (size_t)bl * 32768;
;             {
;                 u32x4 v[8];
; #pragma unroll
;                 for (int i = 0; i < 4; ++i) { v[i] = *(const u32x4*)(cc + (unsigned)((tid + 512 * i) * 8)); v[4 + i] = *(const u32x4*)(bc + (unsigned)((tid + 512 * i) * 8)); }
; #pragma unroll
;                 for (int i = 0; i < 4; ++i) { const int p = tid + 512 * i, r = p >> 4, cp = (p & 15) ^ (r & 15);
;                     *(LAS u32x4*)(Cs + r * 256 + cp * 16) = v[i]; *(LAS u32x4*)(Bs + r * 256 + cp * 16) = v[4 + i]; }
;             }
;             asm volatile("" ::: "memory");
;             {
;                 u32x4 v[8];
; #pragma unroll
;                 for (int i = 0; i < 8; ++i) v[i] = *(const u32x4*)(xt + (unsigned)((tid + 512 * i) * 8));
; #pragma unroll
;                 for (int i = 0; i < 8; ++i) { const int p = tid + 512 * i, r = p >> 4, cp = (p & 15) ^ (r & 15); *(LAS u32x4*)(XTs + r * 256 + cp * 16) = v[i]; }
;             }
.LBB0_957:
	s_ashr_i32 s43, s42, 31
	s_lshl_b64 s[4:5], s[42:43], 16
	v_lshl_add_u64 v[2:3], v[178:179], 0, s[4:5]
	global_load_dwordx4 v[98:101], v[2:3], off
	global_load_dwordx4 v[94:97], v[2:3], off offset:32
	global_load_dwordx4 v[90:93], v[2:3], off offset:64
	global_load_dwordx4 v[86:89], v[2:3], off offset:96
	global_load_dwordx4 v[82:85], v[2:3], off offset:128
	global_load_dwordx4 v[78:81], v[2:3], off offset:160
	global_load_dwordx4 v[74:77], v[2:3], off offset:192
	global_load_dwordx4 v[66:69], v[2:3], off offset:224
	v_add_co_u32_e32 v2, vcc, 0x2000, v2
	s_and_b32 s19, s42, 7
	s_nop 0
	v_addc_co_u32_e32 v3, vcc, 0, v3, vcc
	v_mov_b32_e32 v8, v221
	s_lshl_b64 s[20:21], s[42:43], 15
	global_load_dwordx4 v[18:21], v[2:3], off
	global_load_dwordx4 v[34:37], v[2:3], off offset:32
	global_load_dwordx4 v[38:41], v[2:3], off offset:64
	global_load_dwordx4 v[42:45], v[2:3], off offset:96
	global_load_dwordx4 v[46:49], v[2:3], off offset:128
	global_load_dwordx4 v[134:137], v[2:3], off offset:160
	global_load_dwordx4 v[138:141], v[2:3], off offset:192
	global_load_dwordx4 v[70:73], v[2:3], off offset:224
	s_add_u32 s26, s8, s20
	v_lshlrev_b32_e32 v0, 3, v8
	s_addc_u32 s27, s9, s21
	v_add_u32_e32 v54, 0x3000, v0
	v_mov_b32_e32 v55, v1
	s_add_u32 s20, s10, s20
	v_lshlrev_b64 v[2:3], 1, v[0:1]
	v_lshlrev_b64 v[62:63], 1, v[54:55]
	s_addc_u32 s21, s11, s21
	v_lshl_add_u64 v[4:5], s[26:27], 0, v[2:3]
	v_lshl_add_u64 v[54:55], s[26:27], 0, v[62:63]
	global_load_dwordx4 v[10:13], v[4:5], off
	v_lshl_add_u64 v[58:59], s[20:21], 0, v[62:63]
	global_load_dwordx4 v[54:57], v[54:55], off
	v_lshl_add_u64 v[4:5], s[20:21], 0, v[2:3]
	global_load_dwordx4 v[14:17], v[4:5], off
	v_ashrrev_i32_e32 v9, 4, v8
	global_load_dwordx4 v[58:61], v[58:59], off
	v_add_u32_e32 v4, 0x1000, v0
	v_mov_b32_e32 v5, v1
	v_lshlrev_b64 v[4:5], 1, v[4:5]
	v_lshl_add_u64 v[6:7], s[26:27], 0, v[4:5]
	global_load_dwordx4 v[22:25], v[6:7], off
	v_lshl_add_u64 v[6:7], s[20:21], 0, v[4:5]
	global_load_dwordx4 v[26:29], v[6:7], off
	v_add_u32_e32 v6, 0x2000, v0
	v_mov_b32_e32 v7, v1
	v_lshlrev_b64 v[6:7], 1, v[6:7]
	v_lshl_add_u64 v[30:31], s[26:27], 0, v[6:7]
	global_load_dwordx4 v[30:33], v[30:31], off
	v_lshl_add_u64 v[50:51], s[20:21], 0, v[6:7]
	global_load_dwordx4 v[50:53], v[50:51], off
	v_xor_b32_e32 v64, v9, v8
	v_lshlrev_b32_e32 v64, 4, v64
	v_lshlrev_b32_e32 v9, 8, v9
	v_and_b32_e32 v64, 0xf0, v64
	v_add3_u32 v65, 0, v9, v64
	s_add_u32 s4, s12, s4
	s_addc_u32 s5, s13, s5
	v_lshl_add_u64 v[2:3], s[4:5], 0, v[2:3]
	v_lshl_add_u64 v[6:7], s[4:5], 0, v[6:7]
	s_add_i32 s2, 0, 0x10000
	s_andn2_b64 vcc, exec, s[86:87]
	global_load_dwordx4 v[108:111], v[2:3], off
	global_load_dwordx4 v[112:115], v[6:7], off
	v_lshl_add_u64 v[2:3], s[4:5], 0, v[4:5]
	global_load_dwordx4 v[116:119], v[2:3], off
	v_lshl_add_u64 v[6:7], s[4:5], 0, v[62:63]
	global_load_dwordx4 v[120:123], v[6:7], off
	v_add_u32_e32 v6, 0x4000, v0
	v_mov_b32_e32 v7, v1
	v_lshl_add_u64 v[6:7], v[6:7], 1, s[4:5]
	global_load_dwordx4 v[124:127], v[6:7], off
	v_add_u32_e32 v6, 0x5000, v0
	v_mov_b32_e32 v7, v1
	v_lshl_add_u64 v[6:7], v[6:7], 1, s[4:5]
	global_load_dwordx4 v[128:131], v[6:7], off
	v_add_u32_e32 v6, 0x6000, v0
	v_mov_b32_e32 v7, v1
	v_lshl_add_u64 v[6:7], v[6:7], 1, s[4:5]
	global_load_dwordx4 v[144:147], v[6:7], off
	v_add_u32_e32 v0, 0x7000, v0
	v_lshl_add_u64 v[6:7], v[0:1], 1, s[4:5]
	global_load_dwordx4 v[148:151], v[6:7], off
	s_waitcnt vmcnt(15)
	ds_write_b128 v65, v[10:13]
	s_waitcnt vmcnt(13)
	ds_write_b128 v65, v[14:17] offset:32768
	v_add_u32_e32 v10, 0x200, v8
	v_ashrrev_i32_e32 v10, 4, v10
	v_xor_b32_e32 v11, v10, v8
	v_lshlrev_b32_e32 v65, 8, v10
	v_lshlrev_b32_e32 v10, 4, v11
	v_and_b32_e32 v102, 0xf0, v10
	v_add3_u32 v10, 0, v65, v102
	s_waitcnt vmcnt(11)
	ds_write_b128 v10, v[22:25]
	s_waitcnt vmcnt(10)
	ds_write_b128 v10, v[26:29] offset:32768
	v_add_u32_e32 v10, 0x400, v8
	v_ashrrev_i32_e32 v10, 4, v10
	v_xor_b32_e32 v11, v10, v8
	v_lshlrev_b32_e32 v103, 8, v10
	v_lshlrev_b32_e32 v10, 4, v11
	v_and_b32_e32 v104, 0xf0, v10
	v_add3_u32 v10, 0, v103, v104
	s_waitcnt vmcnt(9)
	ds_write_b128 v10, v[30:33]
	s_waitcnt vmcnt(8)
	ds_write_b128 v10, v[50:53] offset:32768
	v_add_u32_e32 v10, 0x600, v8
	v_ashrrev_i32_e32 v10, 4, v10
	v_xor_b32_e32 v11, v10, v8
	v_lshlrev_b32_e32 v105, 8, v10
	v_lshlrev_b32_e32 v10, 4, v11
	v_and_b32_e32 v106, 0xf0, v10
	v_add3_u32 v10, 0, v105, v106
	ds_write_b128 v10, v[54:57]
	ds_write_b128 v10, v[58:61] offset:32768
	v_add3_u32 v0, s2, v9, v64
	s_mov_b64 s[4:5], -1
	s_waitcnt vmcnt(7)
	ds_write_b128 v0, v[108:111]
	v_add3_u32 v0, s2, v65, v102
	s_waitcnt vmcnt(5)
	ds_write_b128 v0, v[116:119]
	v_add3_u32 v0, s2, v103, v104
	ds_write_b128 v0, v[112:115]
	v_add3_u32 v0, s2, v105, v106
	s_waitcnt vmcnt(4)
	ds_write_b128 v0, v[120:123]
	v_add_u32_e32 v0, 0x800, v8
	v_ashrrev_i32_e32 v0, 4, v0
	v_xor_b32_e32 v2, v0, v8
	v_lshlrev_b32_e32 v2, 4, v2
	v_lshlrev_b32_e32 v0, 8, v0
	v_and_b32_e32 v2, 0xf0, v2
	v_add3_u32 v0, s2, v0, v2
	s_waitcnt vmcnt(3)
	ds_write_b128 v0, v[124:127]
	v_add_u32_e32 v0, 0xa00, v8
	v_ashrrev_i32_e32 v0, 4, v0
	v_xor_b32_e32 v2, v0, v8
	v_lshlrev_b32_e32 v2, 4, v2
	v_lshlrev_b32_e32 v0, 8, v0
	v_and_b32_e32 v2, 0xf0, v2
	v_add3_u32 v0, s2, v0, v2
	s_waitcnt vmcnt(2)
	ds_write_b128 v0, v[128:131]
	v_add_u32_e32 v0, 0xc00, v8
	v_ashrrev_i32_e32 v0, 4, v0
	v_xor_b32_e32 v2, v0, v8
	v_lshlrev_b32_e32 v2, 4, v2
	v_lshlrev_b32_e32 v0, 8, v0
	v_and_b32_e32 v2, 0xf0, v2
	v_add3_u32 v0, s2, v0, v2
	s_waitcnt vmcnt(1)
	ds_write_b128 v0, v[144:147]
	v_add_u32_e32 v0, 0xe00, v8
	v_ashrrev_i32_e32 v0, 4, v0
	v_xor_b32_e32 v2, v0, v8
	v_lshlrev_b32_e32 v2, 4, v2
	v_lshlrev_b32_e32 v0, 8, v0
	v_and_b32_e32 v2, 0xf0, v2
	v_add3_u32 v0, s2, v0, v2
	s_waitcnt vmcnt(0)
	ds_write_b128 v0, v[148:151]
	s_cbranch_vccnz .LBB0_959
	s_lshl_b32 s21, s19, 2
	s_mov_b64 s[4:5], 0
